# chunk-end vmcnt fix (A-loads older than B ring: vmcnt 18/17/16 instead of draining) on all 10 chunked GEMM sites + earlier epilogue/st_bf16/K-loop patches
# speedup vs baseline: 1.1738x; 1.0262x over previous
; DI void lds_barrier() { asm volatile("s_waitcnt lgkmcnt(0)\n\ts_barrier" ::: "memory"); }
;     ...
;             if (c + 1 < NCH) {
;                 unsigned char* wb = lds + ((c + 1) & 1) * A_BUF;
; #pragma unroll
;                 for (int i = 0; i < MT; ++i) { const int idx = i * NTHR + tid, row = idx >> 4, seg = idx & 15; *(u32x4*)(wb + row * A_LD + seg * 16) = areg[i]; }
;             }
;             lds_barrier();
.LBB0_179:
	s_bitcmp1_b32 s34, 0
	s_cselect_b32 s10, 0x6600, 0
	v_or_b32_e32 v1, s10, v206
	v_add_u32_e32 v2, v1, v208
	v_add_u32_e32 v3, v1, v209
	v_add_u32_e32 v1, v1, v210
	s_cmp_eq_u64 s[4:5], 0
	s_cbranch_scc1 .Lcw_a03_slow
	s_waitcnt vmcnt(18)
	ds_write_b128 v2, v[112:115]
	s_waitcnt vmcnt(17)
	ds_write_b128 v3, v[116:119]
	s_waitcnt vmcnt(16)
	ds_write_b128 v1, v[120:123]
	s_branch .LBB0_173
.Lcw_a03_slow:
	s_waitcnt vmcnt(2)
	ds_write_b128 v2, v[112:115]
	s_waitcnt vmcnt(1)
	ds_write_b128 v3, v[116:119]
	s_waitcnt vmcnt(0)
	ds_write_b128 v1, v[120:123]
	s_branch .LBB0_173

; DI void lds_barrier() { asm volatile("s_waitcnt lgkmcnt(0)\n\ts_barrier" ::: "memory"); }
;     ...
;             if (c + 1 < NCH) {
;                 unsigned char* wb = lds + ((c + 1) & 1) * A_BUF;
; #pragma unroll
;                 for (int i = 0; i < MT; ++i) { const int idx = i * NTHR + tid, row = idx >> 4, seg = idx & 15; *(u32x4*)(wb + row * A_LD + seg * 16) = areg[i]; }
;             }
;             lds_barrier();
.LBB0_387:
	s_bitcmp1_b32 s37, 0
	s_cselect_b32 s2, 0x6600, 0
	v_or_b32_e32 v0, s2, v224
	v_add_u32_e32 v2, v0, v226
	v_add_u32_e32 v3, v0, v227
	v_add_u32_e32 v0, v0, v228
	s_cmp_eq_u64 s[4:5], 0
	s_cbranch_scc1 .Lcw_oa3_slow
	s_waitcnt vmcnt(18)
	ds_write_b128 v2, v[112:115]
	s_waitcnt vmcnt(17)
	ds_write_b128 v3, v[116:119]
	s_waitcnt vmcnt(16)
	ds_write_b128 v0, v[120:123]
	s_branch .LBB0_381
.Lcw_oa3_slow:
	s_waitcnt vmcnt(2)
	ds_write_b128 v2, v[112:115]
	s_waitcnt vmcnt(1)
	ds_write_b128 v3, v[116:119]
	s_waitcnt vmcnt(0)
	ds_write_b128 v0, v[120:123]
	s_branch .LBB0_381

; DI void lds_barrier() { asm volatile("s_waitcnt lgkmcnt(0)\n\ts_barrier" ::: "memory"); }
;     ...
;             if (c + 1 < NCH) {
;                 unsigned char* wb = lds + ((c + 1) & 1) * A_BUF;
; #pragma unroll
;                 for (int i = 0; i < MT; ++i) { const int idx = i * NTHR + tid, row = idx >> 4, seg = idx & 15; *(u32x4*)(wb + row * A_LD + seg * 16) = areg[i]; }
;             }
;             lds_barrier();
.LBB0_414:
	s_or_b64 exec, exec, s[2:3]
	s_andn2_b64 vcc, exec, s[56:57]
	s_add_i32 s63, s63, 1
	s_mov_b32 s96, s54
	s_mov_b32 s97, 0x18186000
	s_cbranch_vccnz .LBB0_409
	s_bitcmp1_b32 s63, 0
	s_cselect_b32 s2, 0x6600, 0
	v_or_b32_e32 v0, s2, v224
	v_add_u32_e32 v2, v0, v226
	v_add_u32_e32 v3, v0, v227
	v_add_u32_e32 v0, v0, v228
	s_cmp_eq_u64 s[4:5], 0
	s_cbranch_scc1 .Lcw_out3_slow
	s_waitcnt vmcnt(18)
	ds_write_b128 v2, v[112:115]
	s_waitcnt vmcnt(17)
	ds_write_b128 v3, v[116:119]
	s_waitcnt vmcnt(16)
	ds_write_b128 v0, v[120:123]
	s_branch .LBB0_409

; DI void lds_barrier() { asm volatile("s_waitcnt lgkmcnt(0)\n\ts_barrier" ::: "memory"); }
;     ...
;             if (c + 1 < NCH) {
;                 unsigned char* wb = lds + ((c + 1) & 1) * A_BUF;
; #pragma unroll
;                 for (int i = 0; i < MT; ++i) { const int idx = i * NTHR + tid, row = idx >> 4, seg = idx & 15; *(u32x4*)(wb + row * A_LD + seg * 16) = areg[i]; }
;             }
;             lds_barrier();
.LBB0_425:
	s_bitcmp1_b32 s28, 0
	s_cselect_b32 s2, 0x6600, 0
	v_or_b32_e32 v147, s2, v152
	v_add_u32_e32 v149, v147, v154
	v_add_u32_e32 v151, v147, v155
	v_add_u32_e32 v147, v147, v156
	s_cmp_eq_u64 s[4:5], 0
	s_cbranch_scc1 .Lcw_xq3_slow
	s_waitcnt vmcnt(18)
	ds_write_b128 v149, v[98:101]
	s_waitcnt vmcnt(17)
	ds_write_b128 v151, v[102:105]
	s_waitcnt vmcnt(16)
	ds_write_b128 v147, v[106:109]
	s_branch .LBB0_419
.Lcw_xq3_slow:
	s_waitcnt vmcnt(2)
	ds_write_b128 v149, v[98:101]
	s_waitcnt vmcnt(1)
	ds_write_b128 v151, v[102:105]
	s_waitcnt vmcnt(0)
	ds_write_b128 v147, v[106:109]
	s_branch .LBB0_419

; DI void lds_barrier() { asm volatile("s_waitcnt lgkmcnt(0)\n\ts_barrier" ::: "memory"); }
;     ...
;             if (c + 1 < NCH) {
;                 unsigned char* wb = lds + ((c + 1) & 1) * A_BUF;
; #pragma unroll
;                 for (int i = 0; i < MT; ++i) { const int idx = i * NTHR + tid, row = idx >> 4, seg = idx & 15; *(u32x4*)(wb + row * A_LD + seg * 16) = areg[i]; }
;             }
;             lds_barrier();
.LBB0_454:
	s_bitcmp1_b32 s53, 0
	s_cselect_b32 s2, 0x6600, 0
	v_or_b32_e32 v0, s2, v230
	v_add_u32_e32 v2, v0, v232
	v_add_u32_e32 v3, v0, v233
	v_add_u32_e32 v0, v0, v234
	s_cmp_eq_u64 s[4:5], 0
	s_cbranch_scc1 .Lcw_xo3_slow
	s_waitcnt vmcnt(18)
	ds_write_b128 v2, v[112:115]
	s_waitcnt vmcnt(17)
	ds_write_b128 v3, v[116:119]
	s_waitcnt vmcnt(16)
	ds_write_b128 v0, v[120:123]
	s_branch .LBB0_448

; DI void lds_barrier() { asm volatile("s_waitcnt lgkmcnt(0)\n\ts_barrier" ::: "memory"); }
;     ...
;             if (c + 1 < NCH) {
;                 unsigned char* wb = lds + ((c + 1) & 1) * A_BUF;
; #pragma unroll
;                 for (int i = 0; i < MT; ++i) { const int idx = i * NTHR + tid, row = idx >> 4, seg = idx & 15; *(u32x4*)(wb + row * A_LD + seg * 16) = areg[i]; }
;             }
;             lds_barrier();
.LBB0_813:
	s_bitcmp1_b32 s60, 0
	s_cselect_b32 s2, 0x6600, 0
	v_or_b32_e32 v0, s2, v224
	v_add_u32_e32 v2, v0, v226
	v_add_u32_e32 v3, v0, v227
	v_add_u32_e32 v0, v0, v228
	s_cmp_eq_u64 s[6:7], 0
	s_cbranch_scc1 .Lcw_down3_slow
	s_waitcnt vmcnt(18)
	ds_write_b128 v2, v[112:115]
	s_waitcnt vmcnt(17)
	ds_write_b128 v3, v[116:119]
	s_waitcnt vmcnt(16)
	ds_write_b128 v0, v[120:123]
	s_branch .LBB0_807

; DI void lds_barrier() { asm volatile("s_waitcnt lgkmcnt(0)\n\ts_barrier" ::: "memory"); }
;     ...
;             if (c + 1 < NCH) {
;                 unsigned char* wb = lds + ((c + 1) & 1) * A_BUF;
; #pragma unroll
;                 for (int i = 0; i < MT; ++i) { const int idx = i * NTHR + tid, row = idx >> 4, seg = idx & 15; *(u32x4*)(wb + row * A_LD + seg * 16) = areg[i]; }
;             }
;             lds_barrier();
.LBB0_832:
	s_bitcmp1_b32 s56, 0
	s_cselect_b32 s2, 0x6600, 0
	v_or_b32_e32 v0, s2, v224
	v_add_u32_e32 v2, v0, v226
	v_add_u32_e32 v3, v0, v227
	v_add_u32_e32 v0, v0, v228
	s_cmp_eq_u64 s[6:7], 0
	s_cbranch_scc1 .Lcw_a3_slow
	s_waitcnt vmcnt(18)
	ds_write_b128 v2, v[112:115]
	s_waitcnt vmcnt(17)
	ds_write_b128 v3, v[116:119]
	s_waitcnt vmcnt(16)
	ds_write_b128 v0, v[120:123]
	s_branch .LBB0_826

; DI void lds_barrier() { asm volatile("s_waitcnt lgkmcnt(0)\n\ts_barrier" ::: "memory"); }
;     ...
;             if (c + 1 < NCH) {
;                 unsigned char* wb = lds + ((c + 1) & 1) * A_BUF;
; #pragma unroll
;                 for (int i = 0; i < MT; ++i) { const int idx = i * NTHR + tid, row = idx >> 4, seg = idx & 15; *(u32x4*)(wb + row * A_LD + seg * 16) = areg[i]; }
;             }
;             lds_barrier();
.LBB0_878:
	s_bitcmp1_b32 s53, 0
	s_cselect_b32 s2, 0x6600, 0
	v_or_b32_e32 v0, s2, v137
	v_add_u32_e32 v2, v0, v139
	v_add_u32_e32 v0, v0, v140
	s_cmp_eq_u64 s[6:7], 0
	s_cbranch_scc1 .Lcw_down2_slow
	s_waitcnt vmcnt(17)
	ds_write_b128 v2, v[80:83]
	s_waitcnt vmcnt(16)
	ds_write_b128 v0, v[84:87]
	s_branch .LBB0_872
.Lcw_down2_slow:
	s_waitcnt vmcnt(1)
	ds_write_b128 v2, v[80:83]
	s_waitcnt vmcnt(0)
	ds_write_b128 v0, v[84:87]
	s_branch .LBB0_872
